# v11 + hand-written gate/up epilogue (packed math) + row-ssq prefetch in last K iteration
# speedup vs baseline: 1.0061x; 1.0061x over previous
; __device__ __forceinline__ float siluf_(float x) { return x * sigmoidf_(x); }
; __device__ __forceinline__ float rinv_of(float ssq) { return rsqrtf(ssq * (1.0f / 1024.0f) + EPS); }
; __device__ __forceinline__ u32x4 pack8(const f32x4 a, const f32x4 b) { u32x4 w; w.x = cvt_pk_bf16(a[0], a[1]); w.y = cvt_pk_bf16(a[2], a[3]); w.z = cvt_pk_bf16(b[0], b[1]); w.w = cvt_pk_bf16(b[2], b[3]); return w; }
;     __device__ __forceinline__ void operator()(const AccT& acc, const pg8::Unit& u, int wr, int wc, int fr, int fq) const {
;         asm volatile("" : "+v"(fr), "+v"(fq), "+s"(wr), "+s"(wc));
;         float ris[2][4];
; #pragma unroll
;         for (int ai = 0; ai < 2; ++ai)
; #pragma unroll
;             for (int m = 0; m < 4; ++m) ris[ai][m] = ssq_in[EPI_ROW(u, ai, m)];
; #pragma unroll
;         for (int ai = 0; ai < 2; ++ai)
; #pragma unroll
;             for (int m = 0; m < 4; ++m) {
;                 const int r = EPI_ROW(u, ai, m); const float ri = rinv_of(ris[ai][m]);
;                 f32x4 o[2];
; #pragma unroll
;                 for (int n = 0; n < 2; ++n) { const f32x4 gt = acc[ai][0][m][n] * ri, up = acc[ai][1][m][n] * ri;
; #pragma unroll
;                     for (int j = 0; j < 4; ++j) o[n][j] = siluf_(gt[j]) * up[j]; }
;                 *(u32x4*)(act + (size_t)r * DFF + u.pn * 128 + wc * 32 + 8 * fq) = pack8(o[0], o[1]); }
.LBB0_1535:
	s_lshl_b32 s98, s24, 8
	s_lshl_b32 s99, s35, 6
	s_add_i32 s98, s98, s99
	v_add_u32_e32 v160, s98, v148
	v_lshlrev_b32_e32 v168, 2, v160
	s_waitcnt vmcnt(16)
	s_lshl_b32 s98, s25, 7
	s_lshl_b32 s99, s42, 5
	s_add_i32 s98, s98, s99
	v_lshl_add_u32 v161, v149, 3, s98
	v_lshlrev_b32_e32 v161, 1, v161
	v_mul_u32_u24_e32 v169, 0x1600, v160
	v_add_u32_e32 v161, v161, v169
	s_add_u32 s100, s54, 0x9a2dc00
	s_addc_u32 s101, s55, 0
	v_mov_b32_e32 v188, 0x358637bd
	v_fmamk_f32 v162, v248, 0x3a800000, v188
	v_rsq_f32_e32 v162, v162
	v_mov_b32_e32 v168, v161
	v_pk_mul_f32 v[116:117], v[116:117], v[162:163] op_sel_hi:[1,0]
	v_pk_mul_f32 v[124:125], v[124:125], v[162:163] op_sel_hi:[1,0]
	v_pk_mul_f32 v[118:119], v[118:119], v[162:163] op_sel_hi:[1,0]
	v_pk_mul_f32 v[126:127], v[126:127], v[162:163] op_sel_hi:[1,0]
	v_mul_f32_e32 v164, 0xbfb8aa3b, v116
	v_mul_f32_e32 v165, 0xbfb8aa3b, v117
	v_mul_f32_e32 v166, 0xbfb8aa3b, v118
	v_mul_f32_e32 v167, 0xbfb8aa3b, v119
	v_exp_f32_e32 v164, v164
	v_exp_f32_e32 v165, v165
	v_exp_f32_e32 v166, v166
	v_exp_f32_e32 v167, v167
	v_add_f32_e32 v164, 1.0, v164
	v_add_f32_e32 v165, 1.0, v165
	v_add_f32_e32 v166, 1.0, v166
	v_add_f32_e32 v167, 1.0, v167
	v_rcp_f32_e32 v164, v164
	v_rcp_f32_e32 v165, v165
	v_rcp_f32_e32 v166, v166
	v_rcp_f32_e32 v167, v167
	s_nop 0
	v_pk_mul_f32 v[116:117], v[116:117], v[164:165]
	v_pk_mul_f32 v[118:119], v[118:119], v[166:167]
	v_pk_mul_f32 v[116:117], v[116:117], v[124:125]
	v_pk_mul_f32 v[118:119], v[118:119], v[126:127]
	v_pk_mul_f32 v[112:113], v[112:113], v[162:163] op_sel_hi:[1,0]
	v_pk_mul_f32 v[120:121], v[120:121], v[162:163] op_sel_hi:[1,0]
	v_pk_mul_f32 v[114:115], v[114:115], v[162:163] op_sel_hi:[1,0]
	v_pk_mul_f32 v[122:123], v[122:123], v[162:163] op_sel_hi:[1,0]
	v_mul_f32_e32 v164, 0xbfb8aa3b, v112
	v_mul_f32_e32 v165, 0xbfb8aa3b, v113
	v_mul_f32_e32 v166, 0xbfb8aa3b, v114
	v_mul_f32_e32 v167, 0xbfb8aa3b, v115
	v_exp_f32_e32 v164, v164
	v_exp_f32_e32 v165, v165
	v_exp_f32_e32 v166, v166
	v_exp_f32_e32 v167, v167
	v_add_f32_e32 v164, 1.0, v164
	v_add_f32_e32 v165, 1.0, v165
	v_add_f32_e32 v166, 1.0, v166
	v_add_f32_e32 v167, 1.0, v167
	v_rcp_f32_e32 v164, v164
	v_rcp_f32_e32 v165, v165
	v_rcp_f32_e32 v166, v166
	v_rcp_f32_e32 v167, v167
	s_nop 0
	v_pk_mul_f32 v[112:113], v[112:113], v[164:165]
	v_pk_mul_f32 v[114:115], v[114:115], v[166:167]
	v_pk_mul_f32 v[112:113], v[112:113], v[120:121]
	v_pk_mul_f32 v[114:115], v[114:115], v[122:123]
	v_cvt_pk_bf16_f32 v172, v116, v117
	v_cvt_pk_bf16_f32 v173, v118, v119
	v_cvt_pk_bf16_f32 v174, v112, v113
	v_cvt_pk_bf16_f32 v175, v114, v115
	global_store_dwordx4 v168, v[172:175], s[100:101]
	v_fmamk_f32 v162, v249, 0x3a800000, v188
	v_rsq_f32_e32 v162, v162
	v_add_u32_e32 v168, 0x16000, v161
	v_pk_mul_f32 v[104:105], v[104:105], v[162:163] op_sel_hi:[1,0]
	v_pk_mul_f32 v[108:109], v[108:109], v[162:163] op_sel_hi:[1,0]
	v_pk_mul_f32 v[106:107], v[106:107], v[162:163] op_sel_hi:[1,0]
	v_pk_mul_f32 v[110:111], v[110:111], v[162:163] op_sel_hi:[1,0]
	v_mul_f32_e32 v164, 0xbfb8aa3b, v104
	v_mul_f32_e32 v165, 0xbfb8aa3b, v105
	v_mul_f32_e32 v166, 0xbfb8aa3b, v106
	v_mul_f32_e32 v167, 0xbfb8aa3b, v107
	v_exp_f32_e32 v164, v164
	v_exp_f32_e32 v165, v165
	v_exp_f32_e32 v166, v166
	v_exp_f32_e32 v167, v167
	v_add_f32_e32 v164, 1.0, v164
	v_add_f32_e32 v165, 1.0, v165
	v_add_f32_e32 v166, 1.0, v166
	v_add_f32_e32 v167, 1.0, v167
	v_rcp_f32_e32 v164, v164
	v_rcp_f32_e32 v165, v165
	v_rcp_f32_e32 v166, v166
	v_rcp_f32_e32 v167, v167
	s_nop 0
	v_pk_mul_f32 v[104:105], v[104:105], v[164:165]
	v_pk_mul_f32 v[106:107], v[106:107], v[166:167]
	v_pk_mul_f32 v[104:105], v[104:105], v[108:109]
	v_pk_mul_f32 v[106:107], v[106:107], v[110:111]
	v_pk_mul_f32 v[96:97], v[96:97], v[162:163] op_sel_hi:[1,0]
	v_pk_mul_f32 v[100:101], v[100:101], v[162:163] op_sel_hi:[1,0]
	v_pk_mul_f32 v[98:99], v[98:99], v[162:163] op_sel_hi:[1,0]
	v_pk_mul_f32 v[102:103], v[102:103], v[162:163] op_sel_hi:[1,0]
	v_mul_f32_e32 v164, 0xbfb8aa3b, v96
	v_mul_f32_e32 v165, 0xbfb8aa3b, v97
	v_mul_f32_e32 v166, 0xbfb8aa3b, v98
	v_mul_f32_e32 v167, 0xbfb8aa3b, v99
	v_exp_f32_e32 v164, v164
	v_exp_f32_e32 v165, v165
	v_exp_f32_e32 v166, v166
	v_exp_f32_e32 v167, v167
	v_add_f32_e32 v164, 1.0, v164
	v_add_f32_e32 v165, 1.0, v165
	v_add_f32_e32 v166, 1.0, v166
	v_add_f32_e32 v167, 1.0, v167
	v_rcp_f32_e32 v164, v164
	v_rcp_f32_e32 v165, v165
	v_rcp_f32_e32 v166, v166
	v_rcp_f32_e32 v167, v167
	s_nop 0
	v_pk_mul_f32 v[96:97], v[96:97], v[164:165]
	v_pk_mul_f32 v[98:99], v[98:99], v[166:167]
	v_pk_mul_f32 v[96:97], v[96:97], v[100:101]
	v_pk_mul_f32 v[98:99], v[98:99], v[102:103]
	v_cvt_pk_bf16_f32 v176, v104, v105
	v_cvt_pk_bf16_f32 v177, v106, v107
	v_cvt_pk_bf16_f32 v178, v96, v97
	v_cvt_pk_bf16_f32 v179, v98, v99
	global_store_dwordx4 v168, v[176:179], s[100:101]
	v_fmamk_f32 v162, v250, 0x3a800000, v188
	v_rsq_f32_e32 v162, v162
	v_add_u32_e32 v168, 0x2c000, v161
	v_pk_mul_f32 v[88:89], v[88:89], v[162:163] op_sel_hi:[1,0]
	v_pk_mul_f32 v[92:93], v[92:93], v[162:163] op_sel_hi:[1,0]
	v_pk_mul_f32 v[90:91], v[90:91], v[162:163] op_sel_hi:[1,0]
	v_pk_mul_f32 v[94:95], v[94:95], v[162:163] op_sel_hi:[1,0]
	v_mul_f32_e32 v164, 0xbfb8aa3b, v88
	v_mul_f32_e32 v165, 0xbfb8aa3b, v89
	v_mul_f32_e32 v166, 0xbfb8aa3b, v90
	v_mul_f32_e32 v167, 0xbfb8aa3b, v91
	v_exp_f32_e32 v164, v164
	v_exp_f32_e32 v165, v165
	v_exp_f32_e32 v166, v166
	v_exp_f32_e32 v167, v167
	v_add_f32_e32 v164, 1.0, v164
	v_add_f32_e32 v165, 1.0, v165
	v_add_f32_e32 v166, 1.0, v166
	v_add_f32_e32 v167, 1.0, v167
	v_rcp_f32_e32 v164, v164
	v_rcp_f32_e32 v165, v165
	v_rcp_f32_e32 v166, v166
	v_rcp_f32_e32 v167, v167
; __device__ __forceinline__ float siluf_(float x) { return x * sigmoidf_(x); }
; __device__ __forceinline__ float rinv_of(float ssq) { return rsqrtf(ssq * (1.0f / 1024.0f) + EPS); }
; __device__ __forceinline__ u32x4 pack8(const f32x4 a, const f32x4 b) { u32x4 w; w.x = cvt_pk_bf16(a[0], a[1]); w.y = cvt_pk_bf16(a[2], a[3]); w.z = cvt_pk_bf16(b[0], b[1]); w.w = cvt_pk_bf16(b[2], b[3]); return w; }
;     __device__ __forceinline__ void operator()(const AccT& acc, const pg8::Unit& u, int wr, int wc, int fr, int fq) const {
;     ...
;             for (int m = 0; m < 4; ++m) {
;                 const int r = EPI_ROW(u, ai, m); const float ri = rinv_of(ris[ai][m]);
;                 f32x4 o[2];
; #pragma unroll
;                 for (int n = 0; n < 2; ++n) { const f32x4 gt = acc[ai][0][m][n] * ri, up = acc[ai][1][m][n] * ri;
; #pragma unroll
;                     for (int j = 0; j < 4; ++j) o[n][j] = siluf_(gt[j]) * up[j]; }
;                 *(u32x4*)(act + (size_t)r * DFF + u.pn * 128 + wc * 32 + 8 * fq) = pack8(o[0], o[1]); }
	s_nop 0
	v_pk_mul_f32 v[88:89], v[88:89], v[164:165]
	v_pk_mul_f32 v[90:91], v[90:91], v[166:167]
	v_pk_mul_f32 v[88:89], v[88:89], v[92:93]
	v_pk_mul_f32 v[90:91], v[90:91], v[94:95]
	v_pk_mul_f32 v[80:81], v[80:81], v[162:163] op_sel_hi:[1,0]
	v_pk_mul_f32 v[84:85], v[84:85], v[162:163] op_sel_hi:[1,0]
	v_pk_mul_f32 v[82:83], v[82:83], v[162:163] op_sel_hi:[1,0]
	v_pk_mul_f32 v[86:87], v[86:87], v[162:163] op_sel_hi:[1,0]
	v_mul_f32_e32 v164, 0xbfb8aa3b, v80
	v_mul_f32_e32 v165, 0xbfb8aa3b, v81
	v_mul_f32_e32 v166, 0xbfb8aa3b, v82
	v_mul_f32_e32 v167, 0xbfb8aa3b, v83
	v_exp_f32_e32 v164, v164
	v_exp_f32_e32 v165, v165
	v_exp_f32_e32 v166, v166
	v_exp_f32_e32 v167, v167
	v_add_f32_e32 v164, 1.0, v164
	v_add_f32_e32 v165, 1.0, v165
	v_add_f32_e32 v166, 1.0, v166
	v_add_f32_e32 v167, 1.0, v167
	v_rcp_f32_e32 v164, v164
	v_rcp_f32_e32 v165, v165
	v_rcp_f32_e32 v166, v166
	v_rcp_f32_e32 v167, v167
	s_nop 0
	v_pk_mul_f32 v[80:81], v[80:81], v[164:165]
	v_pk_mul_f32 v[82:83], v[82:83], v[166:167]
	v_pk_mul_f32 v[80:81], v[80:81], v[84:85]
	v_pk_mul_f32 v[82:83], v[82:83], v[86:87]
	v_cvt_pk_bf16_f32 v172, v88, v89
	v_cvt_pk_bf16_f32 v173, v90, v91
	v_cvt_pk_bf16_f32 v174, v80, v81
	v_cvt_pk_bf16_f32 v175, v82, v83
	global_store_dwordx4 v168, v[172:175], s[100:101]
	v_fmamk_f32 v162, v251, 0x3a800000, v188
	v_rsq_f32_e32 v162, v162
	v_add_u32_e32 v168, 0x42000, v161
	v_pk_mul_f32 v[72:73], v[72:73], v[162:163] op_sel_hi:[1,0]
	v_pk_mul_f32 v[76:77], v[76:77], v[162:163] op_sel_hi:[1,0]
	v_pk_mul_f32 v[74:75], v[74:75], v[162:163] op_sel_hi:[1,0]
	v_pk_mul_f32 v[78:79], v[78:79], v[162:163] op_sel_hi:[1,0]
	v_mul_f32_e32 v164, 0xbfb8aa3b, v72
	v_mul_f32_e32 v165, 0xbfb8aa3b, v73
	v_mul_f32_e32 v166, 0xbfb8aa3b, v74
	v_mul_f32_e32 v167, 0xbfb8aa3b, v75
	v_exp_f32_e32 v164, v164
	v_exp_f32_e32 v165, v165
	v_exp_f32_e32 v166, v166
	v_exp_f32_e32 v167, v167
	v_add_f32_e32 v164, 1.0, v164
	v_add_f32_e32 v165, 1.0, v165
	v_add_f32_e32 v166, 1.0, v166
	v_add_f32_e32 v167, 1.0, v167
	v_rcp_f32_e32 v164, v164
	v_rcp_f32_e32 v165, v165
	v_rcp_f32_e32 v166, v166
	v_rcp_f32_e32 v167, v167
	s_nop 0
	v_pk_mul_f32 v[72:73], v[72:73], v[164:165]
	v_pk_mul_f32 v[74:75], v[74:75], v[166:167]
	v_pk_mul_f32 v[72:73], v[72:73], v[76:77]
	v_pk_mul_f32 v[74:75], v[74:75], v[78:79]
	v_pk_mul_f32 v[64:65], v[64:65], v[162:163] op_sel_hi:[1,0]
	v_pk_mul_f32 v[68:69], v[68:69], v[162:163] op_sel_hi:[1,0]
	v_pk_mul_f32 v[66:67], v[66:67], v[162:163] op_sel_hi:[1,0]
	v_pk_mul_f32 v[70:71], v[70:71], v[162:163] op_sel_hi:[1,0]
	v_mul_f32_e32 v164, 0xbfb8aa3b, v64
	v_mul_f32_e32 v165, 0xbfb8aa3b, v65
	v_mul_f32_e32 v166, 0xbfb8aa3b, v66
	v_mul_f32_e32 v167, 0xbfb8aa3b, v67
	v_exp_f32_e32 v164, v164
	v_exp_f32_e32 v165, v165
	v_exp_f32_e32 v166, v166
	v_exp_f32_e32 v167, v167
	v_add_f32_e32 v164, 1.0, v164
	v_add_f32_e32 v165, 1.0, v165
	v_add_f32_e32 v166, 1.0, v166
	v_add_f32_e32 v167, 1.0, v167
	v_rcp_f32_e32 v164, v164
	v_rcp_f32_e32 v165, v165
	v_rcp_f32_e32 v166, v166
	v_rcp_f32_e32 v167, v167
	s_nop 0
	v_pk_mul_f32 v[64:65], v[64:65], v[164:165]
	v_pk_mul_f32 v[66:67], v[66:67], v[166:167]
	v_pk_mul_f32 v[64:65], v[64:65], v[68:69]
	v_pk_mul_f32 v[66:67], v[66:67], v[70:71]
	v_cvt_pk_bf16_f32 v176, v72, v73
	v_cvt_pk_bf16_f32 v177, v74, v75
	v_cvt_pk_bf16_f32 v178, v64, v65
	v_cvt_pk_bf16_f32 v179, v66, v67
	global_store_dwordx4 v168, v[176:179], s[100:101]
	v_fmamk_f32 v162, v252, 0x3a800000, v188
	v_rsq_f32_e32 v162, v162
	v_add_u32_e32 v168, 0xb0000, v161
	v_pk_mul_f32 v[56:57], v[56:57], v[162:163] op_sel_hi:[1,0]
	v_pk_mul_f32 v[60:61], v[60:61], v[162:163] op_sel_hi:[1,0]
	v_pk_mul_f32 v[58:59], v[58:59], v[162:163] op_sel_hi:[1,0]
	v_pk_mul_f32 v[62:63], v[62:63], v[162:163] op_sel_hi:[1,0]
	v_mul_f32_e32 v164, 0xbfb8aa3b, v56
	v_mul_f32_e32 v165, 0xbfb8aa3b, v57
	v_mul_f32_e32 v166, 0xbfb8aa3b, v58
	v_mul_f32_e32 v167, 0xbfb8aa3b, v59
	v_exp_f32_e32 v164, v164
	v_exp_f32_e32 v165, v165
	v_exp_f32_e32 v166, v166
	v_exp_f32_e32 v167, v167
	v_add_f32_e32 v164, 1.0, v164
	v_add_f32_e32 v165, 1.0, v165
	v_add_f32_e32 v166, 1.0, v166
	v_add_f32_e32 v167, 1.0, v167
	v_rcp_f32_e32 v164, v164
	v_rcp_f32_e32 v165, v165
	v_rcp_f32_e32 v166, v166
	v_rcp_f32_e32 v167, v167
	s_nop 0
	v_pk_mul_f32 v[56:57], v[56:57], v[164:165]
	v_pk_mul_f32 v[58:59], v[58:59], v[166:167]
	v_pk_mul_f32 v[56:57], v[56:57], v[60:61]
	v_pk_mul_f32 v[58:59], v[58:59], v[62:63]
	v_pk_mul_f32 v[48:49], v[48:49], v[162:163] op_sel_hi:[1,0]
	v_pk_mul_f32 v[52:53], v[52:53], v[162:163] op_sel_hi:[1,0]
	v_pk_mul_f32 v[50:51], v[50:51], v[162:163] op_sel_hi:[1,0]
	v_pk_mul_f32 v[54:55], v[54:55], v[162:163] op_sel_hi:[1,0]
	v_mul_f32_e32 v164, 0xbfb8aa3b, v48
	v_mul_f32_e32 v165, 0xbfb8aa3b, v49
	v_mul_f32_e32 v166, 0xbfb8aa3b, v50
	v_mul_f32_e32 v167, 0xbfb8aa3b, v51
	v_exp_f32_e32 v164, v164
	v_exp_f32_e32 v165, v165
	v_exp_f32_e32 v166, v166
	v_exp_f32_e32 v167, v167
	v_add_f32_e32 v164, 1.0, v164
	v_add_f32_e32 v165, 1.0, v165
	v_add_f32_e32 v166, 1.0, v166
	v_add_f32_e32 v167, 1.0, v167
	v_rcp_f32_e32 v164, v164
	v_rcp_f32_e32 v165, v165
	v_rcp_f32_e32 v166, v166
	v_rcp_f32_e32 v167, v167
	s_nop 0
	v_pk_mul_f32 v[48:49], v[48:49], v[164:165]
	v_pk_mul_f32 v[50:51], v[50:51], v[166:167]
	v_pk_mul_f32 v[48:49], v[48:49], v[52:53]
	v_pk_mul_f32 v[50:51], v[50:51], v[54:55]
	v_cvt_pk_bf16_f32 v172, v56, v57
	v_cvt_pk_bf16_f32 v173, v58, v59
	v_cvt_pk_bf16_f32 v174, v48, v49
	v_cvt_pk_bf16_f32 v175, v50, v51
	global_store_dwordx4 v168, v[172:175], s[100:101]
	v_fmamk_f32 v162, v253, 0x3a800000, v188
	v_rsq_f32_e32 v162, v162
	v_add_u32_e32 v168, 0xc6000, v161
	v_pk_mul_f32 v[40:41], v[40:41], v[162:163] op_sel_hi:[1,0]
; __device__ __forceinline__ float siluf_(float x) { return x * sigmoidf_(x); }
; __device__ __forceinline__ float rinv_of(float ssq) { return rsqrtf(ssq * (1.0f / 1024.0f) + EPS); }
; __device__ __forceinline__ u32x4 pack8(const f32x4 a, const f32x4 b) { u32x4 w; w.x = cvt_pk_bf16(a[0], a[1]); w.y = cvt_pk_bf16(a[2], a[3]); w.z = cvt_pk_bf16(b[0], b[1]); w.w = cvt_pk_bf16(b[2], b[3]); return w; }
;     __device__ __forceinline__ void operator()(const AccT& acc, const pg8::Unit& u, int wr, int wc, int fr, int fq) const {
;     ...
;             for (int m = 0; m < 4; ++m) {
;                 const int r = EPI_ROW(u, ai, m); const float ri = rinv_of(ris[ai][m]);
;                 f32x4 o[2];
; #pragma unroll
;                 for (int n = 0; n < 2; ++n) { const f32x4 gt = acc[ai][0][m][n] * ri, up = acc[ai][1][m][n] * ri;
; #pragma unroll
;                     for (int j = 0; j < 4; ++j) o[n][j] = siluf_(gt[j]) * up[j]; }
;                 *(u32x4*)(act + (size_t)r * DFF + u.pn * 128 + wc * 32 + 8 * fq) = pack8(o[0], o[1]); }
	v_pk_mul_f32 v[44:45], v[44:45], v[162:163] op_sel_hi:[1,0]
	v_pk_mul_f32 v[42:43], v[42:43], v[162:163] op_sel_hi:[1,0]
	v_pk_mul_f32 v[46:47], v[46:47], v[162:163] op_sel_hi:[1,0]
	v_mul_f32_e32 v164, 0xbfb8aa3b, v40
	v_mul_f32_e32 v165, 0xbfb8aa3b, v41
	v_mul_f32_e32 v166, 0xbfb8aa3b, v42
	v_mul_f32_e32 v167, 0xbfb8aa3b, v43
	v_exp_f32_e32 v164, v164
	v_exp_f32_e32 v165, v165
	v_exp_f32_e32 v166, v166
	v_exp_f32_e32 v167, v167
	v_add_f32_e32 v164, 1.0, v164
	v_add_f32_e32 v165, 1.0, v165
	v_add_f32_e32 v166, 1.0, v166
	v_add_f32_e32 v167, 1.0, v167
	v_rcp_f32_e32 v164, v164
	v_rcp_f32_e32 v165, v165
	v_rcp_f32_e32 v166, v166
	v_rcp_f32_e32 v167, v167
	s_nop 0
	v_pk_mul_f32 v[40:41], v[40:41], v[164:165]
	v_pk_mul_f32 v[42:43], v[42:43], v[166:167]
	v_pk_mul_f32 v[40:41], v[40:41], v[44:45]
	v_pk_mul_f32 v[42:43], v[42:43], v[46:47]
	v_pk_mul_f32 v[32:33], v[32:33], v[162:163] op_sel_hi:[1,0]
	v_pk_mul_f32 v[36:37], v[36:37], v[162:163] op_sel_hi:[1,0]
	v_pk_mul_f32 v[34:35], v[34:35], v[162:163] op_sel_hi:[1,0]
	v_pk_mul_f32 v[38:39], v[38:39], v[162:163] op_sel_hi:[1,0]
	v_mul_f32_e32 v164, 0xbfb8aa3b, v32
	v_mul_f32_e32 v165, 0xbfb8aa3b, v33
	v_mul_f32_e32 v166, 0xbfb8aa3b, v34
	v_mul_f32_e32 v167, 0xbfb8aa3b, v35
	v_exp_f32_e32 v164, v164
	v_exp_f32_e32 v165, v165
	v_exp_f32_e32 v166, v166
	v_exp_f32_e32 v167, v167
	v_add_f32_e32 v164, 1.0, v164
	v_add_f32_e32 v165, 1.0, v165
	v_add_f32_e32 v166, 1.0, v166
	v_add_f32_e32 v167, 1.0, v167
	v_rcp_f32_e32 v164, v164
	v_rcp_f32_e32 v165, v165
	v_rcp_f32_e32 v166, v166
	v_rcp_f32_e32 v167, v167
	s_nop 0
	v_pk_mul_f32 v[32:33], v[32:33], v[164:165]
	v_pk_mul_f32 v[34:35], v[34:35], v[166:167]
	v_pk_mul_f32 v[32:33], v[32:33], v[36:37]
	v_pk_mul_f32 v[34:35], v[34:35], v[38:39]
	v_cvt_pk_bf16_f32 v176, v40, v41
	v_cvt_pk_bf16_f32 v177, v42, v43
	v_cvt_pk_bf16_f32 v178, v32, v33
	v_cvt_pk_bf16_f32 v179, v34, v35
	global_store_dwordx4 v168, v[176:179], s[100:101]
	v_fmamk_f32 v162, v254, 0x3a800000, v188
	v_rsq_f32_e32 v162, v162
	v_add_u32_e32 v168, 0xdc000, v161
	v_pk_mul_f32 v[24:25], v[24:25], v[162:163] op_sel_hi:[1,0]
	v_pk_mul_f32 v[28:29], v[28:29], v[162:163] op_sel_hi:[1,0]
	v_pk_mul_f32 v[26:27], v[26:27], v[162:163] op_sel_hi:[1,0]
	v_pk_mul_f32 v[30:31], v[30:31], v[162:163] op_sel_hi:[1,0]
	v_mul_f32_e32 v164, 0xbfb8aa3b, v24
	v_mul_f32_e32 v165, 0xbfb8aa3b, v25
	v_mul_f32_e32 v166, 0xbfb8aa3b, v26
	v_mul_f32_e32 v167, 0xbfb8aa3b, v27
	v_exp_f32_e32 v164, v164
	v_exp_f32_e32 v165, v165
	v_exp_f32_e32 v166, v166
	v_exp_f32_e32 v167, v167
	v_add_f32_e32 v164, 1.0, v164
	v_add_f32_e32 v165, 1.0, v165
	v_add_f32_e32 v166, 1.0, v166
	v_add_f32_e32 v167, 1.0, v167
	v_rcp_f32_e32 v164, v164
	v_rcp_f32_e32 v165, v165
	v_rcp_f32_e32 v166, v166
	v_rcp_f32_e32 v167, v167
	s_nop 0
	v_pk_mul_f32 v[24:25], v[24:25], v[164:165]
	v_pk_mul_f32 v[26:27], v[26:27], v[166:167]
	v_pk_mul_f32 v[24:25], v[24:25], v[28:29]
	v_pk_mul_f32 v[26:27], v[26:27], v[30:31]
	v_pk_mul_f32 v[16:17], v[16:17], v[162:163] op_sel_hi:[1,0]
	v_pk_mul_f32 v[20:21], v[20:21], v[162:163] op_sel_hi:[1,0]
	v_pk_mul_f32 v[18:19], v[18:19], v[162:163] op_sel_hi:[1,0]
	v_pk_mul_f32 v[22:23], v[22:23], v[162:163] op_sel_hi:[1,0]
	v_mul_f32_e32 v164, 0xbfb8aa3b, v16
	v_mul_f32_e32 v165, 0xbfb8aa3b, v17
	v_mul_f32_e32 v166, 0xbfb8aa3b, v18
	v_mul_f32_e32 v167, 0xbfb8aa3b, v19
	v_exp_f32_e32 v164, v164
	v_exp_f32_e32 v165, v165
	v_exp_f32_e32 v166, v166
	v_exp_f32_e32 v167, v167
	v_add_f32_e32 v164, 1.0, v164
	v_add_f32_e32 v165, 1.0, v165
	v_add_f32_e32 v166, 1.0, v166
	v_add_f32_e32 v167, 1.0, v167
	v_rcp_f32_e32 v164, v164
	v_rcp_f32_e32 v165, v165
	v_rcp_f32_e32 v166, v166
	v_rcp_f32_e32 v167, v167
	s_nop 0
	v_pk_mul_f32 v[16:17], v[16:17], v[164:165]
	v_pk_mul_f32 v[18:19], v[18:19], v[166:167]
	v_pk_mul_f32 v[16:17], v[16:17], v[20:21]
	v_pk_mul_f32 v[18:19], v[18:19], v[22:23]
	v_cvt_pk_bf16_f32 v172, v24, v25
	v_cvt_pk_bf16_f32 v173, v26, v27
	v_cvt_pk_bf16_f32 v174, v16, v17
	v_cvt_pk_bf16_f32 v175, v18, v19
	global_store_dwordx4 v168, v[172:175], s[100:101]
	v_fmamk_f32 v162, v255, 0x3a800000, v188
	v_rsq_f32_e32 v162, v162
	v_add_u32_e32 v168, 0xf2000, v161
	v_pk_mul_f32 v[8:9], v[8:9], v[162:163] op_sel_hi:[1,0]
	v_pk_mul_f32 v[12:13], v[12:13], v[162:163] op_sel_hi:[1,0]
	v_pk_mul_f32 v[10:11], v[10:11], v[162:163] op_sel_hi:[1,0]
	v_pk_mul_f32 v[14:15], v[14:15], v[162:163] op_sel_hi:[1,0]
	v_mul_f32_e32 v164, 0xbfb8aa3b, v8
	v_mul_f32_e32 v165, 0xbfb8aa3b, v9
	v_mul_f32_e32 v166, 0xbfb8aa3b, v10
	v_mul_f32_e32 v167, 0xbfb8aa3b, v11
	v_exp_f32_e32 v164, v164
	v_exp_f32_e32 v165, v165
	v_exp_f32_e32 v166, v166
	v_exp_f32_e32 v167, v167
	v_add_f32_e32 v164, 1.0, v164
	v_add_f32_e32 v165, 1.0, v165
	v_add_f32_e32 v166, 1.0, v166
	v_add_f32_e32 v167, 1.0, v167
	v_rcp_f32_e32 v164, v164
	v_rcp_f32_e32 v165, v165
	v_rcp_f32_e32 v166, v166
	v_rcp_f32_e32 v167, v167
	s_nop 0
	v_pk_mul_f32 v[8:9], v[8:9], v[164:165]
	v_pk_mul_f32 v[10:11], v[10:11], v[166:167]
	v_pk_mul_f32 v[8:9], v[8:9], v[12:13]
	v_pk_mul_f32 v[10:11], v[10:11], v[14:15]
	v_pk_mul_f32 v[4:5], v[4:5], v[162:163] op_sel_hi:[1,0]
	v_pk_mul_f32 v[0:1], v[0:1], v[162:163] op_sel_hi:[1,0]
	v_pk_mul_f32 v[6:7], v[6:7], v[162:163] op_sel_hi:[1,0]
	v_pk_mul_f32 v[2:3], v[2:3], v[162:163] op_sel_hi:[1,0]
	v_mul_f32_e32 v164, 0xbfb8aa3b, v4
	v_mul_f32_e32 v165, 0xbfb8aa3b, v5
	v_mul_f32_e32 v166, 0xbfb8aa3b, v6
	v_mul_f32_e32 v167, 0xbfb8aa3b, v7
	v_exp_f32_e32 v164, v164
	v_exp_f32_e32 v165, v165
	v_exp_f32_e32 v166, v166
	v_exp_f32_e32 v167, v167
	v_add_f32_e32 v164, 1.0, v164
	v_add_f32_e32 v165, 1.0, v165
	v_add_f32_e32 v166, 1.0, v166
	v_add_f32_e32 v167, 1.0, v167
	v_rcp_f32_e32 v164, v164
	v_rcp_f32_e32 v165, v165
	v_rcp_f32_e32 v166, v166
	v_rcp_f32_e32 v167, v167
	s_nop 0
	v_pk_mul_f32 v[4:5], v[4:5], v[164:165]
	v_pk_mul_f32 v[6:7], v[6:7], v[166:167]
	v_pk_mul_f32 v[4:5], v[4:5], v[0:1]
	v_pk_mul_f32 v[6:7], v[6:7], v[2:3]
	v_cvt_pk_bf16_f32 v176, v8, v9
	v_cvt_pk_bf16_f32 v177, v10, v11
	v_cvt_pk_bf16_f32 v178, v4, v5
	v_cvt_pk_bf16_f32 v179, v6, v7
	global_store_dwordx4 v168, v[176:179], s[100:101]
	s_mov_b64 s[28:29], s[18:19]
	s_mov_b32 s25, s14
	s_mov_b32 s24, s16
	s_mov_b64 s[26:27], s[22:23]
	s_and_b64 vcc, exec, s[6:7]
	s_cbranch_vccnz .LBB0_1545

; __device__ __forceinline__ float siluf_(float x) { return x * sigmoidf_(x); }
; __device__ __forceinline__ float rinv_of(float ssq) { return rsqrtf(ssq * (1.0f / 1024.0f) + EPS); }
; __device__ __forceinline__ u32x4 pack8(const f32x4 a, const f32x4 b) { u32x4 w; w.x = cvt_pk_bf16(a[0], a[1]); w.y = cvt_pk_bf16(a[2], a[3]); w.z = cvt_pk_bf16(b[0], b[1]); w.w = cvt_pk_bf16(b[2], b[3]); return w; }
;     __device__ __forceinline__ void operator()(const AccT& acc, const pg8::Unit& u, int wr, int wc, int fr, int fq) const {
;         asm volatile("" : "+v"(fr), "+v"(fq), "+s"(wr), "+s"(wc));
;         float ris[2][4];
; #pragma unroll
;         for (int ai = 0; ai < 2; ++ai)
; #pragma unroll
;             for (int m = 0; m < 4; ++m) ris[ai][m] = ssq_in[EPI_ROW(u, ai, m)];
; #pragma unroll
;         for (int ai = 0; ai < 2; ++ai)
; #pragma unroll
;             for (int m = 0; m < 4; ++m) {
;                 const int r = EPI_ROW(u, ai, m); const float ri = rinv_of(ris[ai][m]);
;                 f32x4 o[2];
; #pragma unroll
;                 for (int n = 0; n < 2; ++n) { const f32x4 gt = acc[ai][0][m][n] * ri, up = acc[ai][1][m][n] * ri;
; #pragma unroll
;                     for (int j = 0; j < 4; ++j) o[n][j] = siluf_(gt[j]) * up[j]; }
;                 *(u32x4*)(act + (size_t)r * DFF + u.pn * 128 + wc * 32 + 8 * fq) = pack8(o[0], o[1]); }
.LBB0_2402:
	s_lshl_b32 s98, s24, 8
	s_lshl_b32 s99, s35, 6
	s_add_i32 s98, s98, s99
	v_add_u32_e32 v160, s98, v148
	v_lshlrev_b32_e32 v168, 2, v160
	s_waitcnt vmcnt(16)
	s_lshl_b32 s98, s25, 7
	s_lshl_b32 s99, s42, 5
	s_add_i32 s98, s98, s99
	v_lshl_add_u32 v161, v149, 3, s98
	v_lshlrev_b32_e32 v161, 1, v161
	v_mul_u32_u24_e32 v169, 0x1600, v160
	v_add_u32_e32 v161, v161, v169
	s_add_u32 s100, s54, 0x9a2dc00
	s_addc_u32 s101, s55, 0
	v_mov_b32_e32 v188, 0x358637bd
	v_fmamk_f32 v162, v248, 0x3a800000, v188
	v_rsq_f32_e32 v162, v162
	v_mov_b32_e32 v168, v161
	v_pk_mul_f32 v[116:117], v[116:117], v[162:163] op_sel_hi:[1,0]
	v_pk_mul_f32 v[124:125], v[124:125], v[162:163] op_sel_hi:[1,0]
	v_pk_mul_f32 v[118:119], v[118:119], v[162:163] op_sel_hi:[1,0]
	v_pk_mul_f32 v[126:127], v[126:127], v[162:163] op_sel_hi:[1,0]
	v_mul_f32_e32 v164, 0xbfb8aa3b, v116
	v_mul_f32_e32 v165, 0xbfb8aa3b, v117
	v_mul_f32_e32 v166, 0xbfb8aa3b, v118
	v_mul_f32_e32 v167, 0xbfb8aa3b, v119
	v_exp_f32_e32 v164, v164
	v_exp_f32_e32 v165, v165
	v_exp_f32_e32 v166, v166
	v_exp_f32_e32 v167, v167
	v_add_f32_e32 v164, 1.0, v164
	v_add_f32_e32 v165, 1.0, v165
	v_add_f32_e32 v166, 1.0, v166
	v_add_f32_e32 v167, 1.0, v167
	v_rcp_f32_e32 v164, v164
	v_rcp_f32_e32 v165, v165
	v_rcp_f32_e32 v166, v166
	v_rcp_f32_e32 v167, v167
	s_nop 0
	v_pk_mul_f32 v[116:117], v[116:117], v[164:165]
	v_pk_mul_f32 v[118:119], v[118:119], v[166:167]
	v_pk_mul_f32 v[116:117], v[116:117], v[124:125]
	v_pk_mul_f32 v[118:119], v[118:119], v[126:127]
	v_pk_mul_f32 v[112:113], v[112:113], v[162:163] op_sel_hi:[1,0]
	v_pk_mul_f32 v[120:121], v[120:121], v[162:163] op_sel_hi:[1,0]
	v_pk_mul_f32 v[114:115], v[114:115], v[162:163] op_sel_hi:[1,0]
	v_pk_mul_f32 v[122:123], v[122:123], v[162:163] op_sel_hi:[1,0]
	v_mul_f32_e32 v164, 0xbfb8aa3b, v112
	v_mul_f32_e32 v165, 0xbfb8aa3b, v113
	v_mul_f32_e32 v166, 0xbfb8aa3b, v114
	v_mul_f32_e32 v167, 0xbfb8aa3b, v115
	v_exp_f32_e32 v164, v164
	v_exp_f32_e32 v165, v165
	v_exp_f32_e32 v166, v166
	v_exp_f32_e32 v167, v167
	v_add_f32_e32 v164, 1.0, v164
	v_add_f32_e32 v165, 1.0, v165
	v_add_f32_e32 v166, 1.0, v166
	v_add_f32_e32 v167, 1.0, v167
	v_rcp_f32_e32 v164, v164
	v_rcp_f32_e32 v165, v165
	v_rcp_f32_e32 v166, v166
	v_rcp_f32_e32 v167, v167
	s_nop 0
	v_pk_mul_f32 v[112:113], v[112:113], v[164:165]
	v_pk_mul_f32 v[114:115], v[114:115], v[166:167]
	v_pk_mul_f32 v[112:113], v[112:113], v[120:121]
	v_pk_mul_f32 v[114:115], v[114:115], v[122:123]
	v_cvt_pk_bf16_f32 v172, v116, v117
	v_cvt_pk_bf16_f32 v173, v118, v119
	v_cvt_pk_bf16_f32 v174, v112, v113
	v_cvt_pk_bf16_f32 v175, v114, v115
	global_store_dwordx4 v168, v[172:175], s[100:101]
	v_fmamk_f32 v162, v249, 0x3a800000, v188
	v_rsq_f32_e32 v162, v162
	v_add_u32_e32 v168, 0x16000, v161
	v_pk_mul_f32 v[104:105], v[104:105], v[162:163] op_sel_hi:[1,0]
	v_pk_mul_f32 v[108:109], v[108:109], v[162:163] op_sel_hi:[1,0]
	v_pk_mul_f32 v[106:107], v[106:107], v[162:163] op_sel_hi:[1,0]
	v_pk_mul_f32 v[110:111], v[110:111], v[162:163] op_sel_hi:[1,0]
	v_mul_f32_e32 v164, 0xbfb8aa3b, v104
	v_mul_f32_e32 v165, 0xbfb8aa3b, v105
	v_mul_f32_e32 v166, 0xbfb8aa3b, v106
	v_mul_f32_e32 v167, 0xbfb8aa3b, v107
	v_exp_f32_e32 v164, v164
	v_exp_f32_e32 v165, v165
	v_exp_f32_e32 v166, v166
	v_exp_f32_e32 v167, v167
	v_add_f32_e32 v164, 1.0, v164
	v_add_f32_e32 v165, 1.0, v165
	v_add_f32_e32 v166, 1.0, v166
	v_add_f32_e32 v167, 1.0, v167
	v_rcp_f32_e32 v164, v164
	v_rcp_f32_e32 v165, v165
	v_rcp_f32_e32 v166, v166
	v_rcp_f32_e32 v167, v167
	s_nop 0
	v_pk_mul_f32 v[104:105], v[104:105], v[164:165]
	v_pk_mul_f32 v[106:107], v[106:107], v[166:167]
	v_pk_mul_f32 v[104:105], v[104:105], v[108:109]
	v_pk_mul_f32 v[106:107], v[106:107], v[110:111]
	v_pk_mul_f32 v[96:97], v[96:97], v[162:163] op_sel_hi:[1,0]
	v_pk_mul_f32 v[100:101], v[100:101], v[162:163] op_sel_hi:[1,0]
	v_pk_mul_f32 v[98:99], v[98:99], v[162:163] op_sel_hi:[1,0]
	v_pk_mul_f32 v[102:103], v[102:103], v[162:163] op_sel_hi:[1,0]
	v_mul_f32_e32 v164, 0xbfb8aa3b, v96
	v_mul_f32_e32 v165, 0xbfb8aa3b, v97
	v_mul_f32_e32 v166, 0xbfb8aa3b, v98
	v_mul_f32_e32 v167, 0xbfb8aa3b, v99
	v_exp_f32_e32 v164, v164
	v_exp_f32_e32 v165, v165
	v_exp_f32_e32 v166, v166
	v_exp_f32_e32 v167, v167
	v_add_f32_e32 v164, 1.0, v164
	v_add_f32_e32 v165, 1.0, v165
	v_add_f32_e32 v166, 1.0, v166
	v_add_f32_e32 v167, 1.0, v167
	v_rcp_f32_e32 v164, v164
	v_rcp_f32_e32 v165, v165
	v_rcp_f32_e32 v166, v166
	v_rcp_f32_e32 v167, v167
	s_nop 0
	v_pk_mul_f32 v[96:97], v[96:97], v[164:165]
	v_pk_mul_f32 v[98:99], v[98:99], v[166:167]
	v_pk_mul_f32 v[96:97], v[96:97], v[100:101]
	v_pk_mul_f32 v[98:99], v[98:99], v[102:103]
	v_cvt_pk_bf16_f32 v176, v104, v105
	v_cvt_pk_bf16_f32 v177, v106, v107
	v_cvt_pk_bf16_f32 v178, v96, v97
	v_cvt_pk_bf16_f32 v179, v98, v99
	global_store_dwordx4 v168, v[176:179], s[100:101]
	v_fmamk_f32 v162, v250, 0x3a800000, v188
	v_rsq_f32_e32 v162, v162
	v_add_u32_e32 v168, 0x2c000, v161
	v_pk_mul_f32 v[88:89], v[88:89], v[162:163] op_sel_hi:[1,0]
	v_pk_mul_f32 v[92:93], v[92:93], v[162:163] op_sel_hi:[1,0]
	v_pk_mul_f32 v[90:91], v[90:91], v[162:163] op_sel_hi:[1,0]
	v_pk_mul_f32 v[94:95], v[94:95], v[162:163] op_sel_hi:[1,0]
	v_mul_f32_e32 v164, 0xbfb8aa3b, v88
	v_mul_f32_e32 v165, 0xbfb8aa3b, v89
	v_mul_f32_e32 v166, 0xbfb8aa3b, v90
	v_mul_f32_e32 v167, 0xbfb8aa3b, v91
	v_exp_f32_e32 v164, v164
	v_exp_f32_e32 v165, v165
	v_exp_f32_e32 v166, v166
	v_exp_f32_e32 v167, v167
	v_add_f32_e32 v164, 1.0, v164
	v_add_f32_e32 v165, 1.0, v165
	v_add_f32_e32 v166, 1.0, v166
	v_add_f32_e32 v167, 1.0, v167
	v_rcp_f32_e32 v164, v164
	v_rcp_f32_e32 v165, v165
	v_rcp_f32_e32 v166, v166
	v_rcp_f32_e32 v167, v167
; __device__ __forceinline__ float siluf_(float x) { return x * sigmoidf_(x); }
; __device__ __forceinline__ float rinv_of(float ssq) { return rsqrtf(ssq * (1.0f / 1024.0f) + EPS); }
; __device__ __forceinline__ u32x4 pack8(const f32x4 a, const f32x4 b) { u32x4 w; w.x = cvt_pk_bf16(a[0], a[1]); w.y = cvt_pk_bf16(a[2], a[3]); w.z = cvt_pk_bf16(b[0], b[1]); w.w = cvt_pk_bf16(b[2], b[3]); return w; }
;     __device__ __forceinline__ void operator()(const AccT& acc, const pg8::Unit& u, int wr, int wc, int fr, int fq) const {
;     ...
;             for (int m = 0; m < 4; ++m) {
;                 const int r = EPI_ROW(u, ai, m); const float ri = rinv_of(ris[ai][m]);
;                 f32x4 o[2];
; #pragma unroll
;                 for (int n = 0; n < 2; ++n) { const f32x4 gt = acc[ai][0][m][n] * ri, up = acc[ai][1][m][n] * ri;
; #pragma unroll
;                     for (int j = 0; j < 4; ++j) o[n][j] = siluf_(gt[j]) * up[j]; }
;                 *(u32x4*)(act + (size_t)r * DFF + u.pn * 128 + wc * 32 + 8 * fq) = pack8(o[0], o[1]); }
	s_nop 0
	v_pk_mul_f32 v[88:89], v[88:89], v[164:165]
	v_pk_mul_f32 v[90:91], v[90:91], v[166:167]
	v_pk_mul_f32 v[88:89], v[88:89], v[92:93]
	v_pk_mul_f32 v[90:91], v[90:91], v[94:95]
	v_pk_mul_f32 v[80:81], v[80:81], v[162:163] op_sel_hi:[1,0]
	v_pk_mul_f32 v[84:85], v[84:85], v[162:163] op_sel_hi:[1,0]
	v_pk_mul_f32 v[82:83], v[82:83], v[162:163] op_sel_hi:[1,0]
	v_pk_mul_f32 v[86:87], v[86:87], v[162:163] op_sel_hi:[1,0]
	v_mul_f32_e32 v164, 0xbfb8aa3b, v80
	v_mul_f32_e32 v165, 0xbfb8aa3b, v81
	v_mul_f32_e32 v166, 0xbfb8aa3b, v82
	v_mul_f32_e32 v167, 0xbfb8aa3b, v83
	v_exp_f32_e32 v164, v164
	v_exp_f32_e32 v165, v165
	v_exp_f32_e32 v166, v166
	v_exp_f32_e32 v167, v167
	v_add_f32_e32 v164, 1.0, v164
	v_add_f32_e32 v165, 1.0, v165
	v_add_f32_e32 v166, 1.0, v166
	v_add_f32_e32 v167, 1.0, v167
	v_rcp_f32_e32 v164, v164
	v_rcp_f32_e32 v165, v165
	v_rcp_f32_e32 v166, v166
	v_rcp_f32_e32 v167, v167
	s_nop 0
	v_pk_mul_f32 v[80:81], v[80:81], v[164:165]
	v_pk_mul_f32 v[82:83], v[82:83], v[166:167]
	v_pk_mul_f32 v[80:81], v[80:81], v[84:85]
	v_pk_mul_f32 v[82:83], v[82:83], v[86:87]
	v_cvt_pk_bf16_f32 v172, v88, v89
	v_cvt_pk_bf16_f32 v173, v90, v91
	v_cvt_pk_bf16_f32 v174, v80, v81
	v_cvt_pk_bf16_f32 v175, v82, v83
	global_store_dwordx4 v168, v[172:175], s[100:101]
	v_fmamk_f32 v162, v251, 0x3a800000, v188
	v_rsq_f32_e32 v162, v162
	v_add_u32_e32 v168, 0x42000, v161
	v_pk_mul_f32 v[72:73], v[72:73], v[162:163] op_sel_hi:[1,0]
	v_pk_mul_f32 v[76:77], v[76:77], v[162:163] op_sel_hi:[1,0]
	v_pk_mul_f32 v[74:75], v[74:75], v[162:163] op_sel_hi:[1,0]
	v_pk_mul_f32 v[78:79], v[78:79], v[162:163] op_sel_hi:[1,0]
	v_mul_f32_e32 v164, 0xbfb8aa3b, v72
	v_mul_f32_e32 v165, 0xbfb8aa3b, v73
	v_mul_f32_e32 v166, 0xbfb8aa3b, v74
	v_mul_f32_e32 v167, 0xbfb8aa3b, v75
	v_exp_f32_e32 v164, v164
	v_exp_f32_e32 v165, v165
	v_exp_f32_e32 v166, v166
	v_exp_f32_e32 v167, v167
	v_add_f32_e32 v164, 1.0, v164
	v_add_f32_e32 v165, 1.0, v165
	v_add_f32_e32 v166, 1.0, v166
	v_add_f32_e32 v167, 1.0, v167
	v_rcp_f32_e32 v164, v164
	v_rcp_f32_e32 v165, v165
	v_rcp_f32_e32 v166, v166
	v_rcp_f32_e32 v167, v167
	s_nop 0
	v_pk_mul_f32 v[72:73], v[72:73], v[164:165]
	v_pk_mul_f32 v[74:75], v[74:75], v[166:167]
	v_pk_mul_f32 v[72:73], v[72:73], v[76:77]
	v_pk_mul_f32 v[74:75], v[74:75], v[78:79]
	v_pk_mul_f32 v[64:65], v[64:65], v[162:163] op_sel_hi:[1,0]
	v_pk_mul_f32 v[68:69], v[68:69], v[162:163] op_sel_hi:[1,0]
	v_pk_mul_f32 v[66:67], v[66:67], v[162:163] op_sel_hi:[1,0]
	v_pk_mul_f32 v[70:71], v[70:71], v[162:163] op_sel_hi:[1,0]
	v_mul_f32_e32 v164, 0xbfb8aa3b, v64
	v_mul_f32_e32 v165, 0xbfb8aa3b, v65
	v_mul_f32_e32 v166, 0xbfb8aa3b, v66
	v_mul_f32_e32 v167, 0xbfb8aa3b, v67
	v_exp_f32_e32 v164, v164
	v_exp_f32_e32 v165, v165
	v_exp_f32_e32 v166, v166
	v_exp_f32_e32 v167, v167
	v_add_f32_e32 v164, 1.0, v164
	v_add_f32_e32 v165, 1.0, v165
	v_add_f32_e32 v166, 1.0, v166
	v_add_f32_e32 v167, 1.0, v167
	v_rcp_f32_e32 v164, v164
	v_rcp_f32_e32 v165, v165
	v_rcp_f32_e32 v166, v166
	v_rcp_f32_e32 v167, v167
	s_nop 0
	v_pk_mul_f32 v[64:65], v[64:65], v[164:165]
	v_pk_mul_f32 v[66:67], v[66:67], v[166:167]
	v_pk_mul_f32 v[64:65], v[64:65], v[68:69]
	v_pk_mul_f32 v[66:67], v[66:67], v[70:71]
	v_cvt_pk_bf16_f32 v176, v72, v73
	v_cvt_pk_bf16_f32 v177, v74, v75
	v_cvt_pk_bf16_f32 v178, v64, v65
	v_cvt_pk_bf16_f32 v179, v66, v67
	global_store_dwordx4 v168, v[176:179], s[100:101]
	v_fmamk_f32 v162, v252, 0x3a800000, v188
	v_rsq_f32_e32 v162, v162
	v_add_u32_e32 v168, 0xb0000, v161
	v_pk_mul_f32 v[56:57], v[56:57], v[162:163] op_sel_hi:[1,0]
	v_pk_mul_f32 v[60:61], v[60:61], v[162:163] op_sel_hi:[1,0]
	v_pk_mul_f32 v[58:59], v[58:59], v[162:163] op_sel_hi:[1,0]
	v_pk_mul_f32 v[62:63], v[62:63], v[162:163] op_sel_hi:[1,0]
	v_mul_f32_e32 v164, 0xbfb8aa3b, v56
	v_mul_f32_e32 v165, 0xbfb8aa3b, v57
	v_mul_f32_e32 v166, 0xbfb8aa3b, v58
	v_mul_f32_e32 v167, 0xbfb8aa3b, v59
	v_exp_f32_e32 v164, v164
	v_exp_f32_e32 v165, v165
	v_exp_f32_e32 v166, v166
	v_exp_f32_e32 v167, v167
	v_add_f32_e32 v164, 1.0, v164
	v_add_f32_e32 v165, 1.0, v165
	v_add_f32_e32 v166, 1.0, v166
	v_add_f32_e32 v167, 1.0, v167
	v_rcp_f32_e32 v164, v164
	v_rcp_f32_e32 v165, v165
	v_rcp_f32_e32 v166, v166
	v_rcp_f32_e32 v167, v167
	s_nop 0
	v_pk_mul_f32 v[56:57], v[56:57], v[164:165]
	v_pk_mul_f32 v[58:59], v[58:59], v[166:167]
	v_pk_mul_f32 v[56:57], v[56:57], v[60:61]
	v_pk_mul_f32 v[58:59], v[58:59], v[62:63]
	v_pk_mul_f32 v[48:49], v[48:49], v[162:163] op_sel_hi:[1,0]
	v_pk_mul_f32 v[52:53], v[52:53], v[162:163] op_sel_hi:[1,0]
	v_pk_mul_f32 v[50:51], v[50:51], v[162:163] op_sel_hi:[1,0]
	v_pk_mul_f32 v[54:55], v[54:55], v[162:163] op_sel_hi:[1,0]
	v_mul_f32_e32 v164, 0xbfb8aa3b, v48
	v_mul_f32_e32 v165, 0xbfb8aa3b, v49
	v_mul_f32_e32 v166, 0xbfb8aa3b, v50
	v_mul_f32_e32 v167, 0xbfb8aa3b, v51
	v_exp_f32_e32 v164, v164
	v_exp_f32_e32 v165, v165
	v_exp_f32_e32 v166, v166
	v_exp_f32_e32 v167, v167
	v_add_f32_e32 v164, 1.0, v164
	v_add_f32_e32 v165, 1.0, v165
	v_add_f32_e32 v166, 1.0, v166
	v_add_f32_e32 v167, 1.0, v167
	v_rcp_f32_e32 v164, v164
	v_rcp_f32_e32 v165, v165
	v_rcp_f32_e32 v166, v166
	v_rcp_f32_e32 v167, v167
	s_nop 0
	v_pk_mul_f32 v[48:49], v[48:49], v[164:165]
	v_pk_mul_f32 v[50:51], v[50:51], v[166:167]
	v_pk_mul_f32 v[48:49], v[48:49], v[52:53]
	v_pk_mul_f32 v[50:51], v[50:51], v[54:55]
	v_cvt_pk_bf16_f32 v172, v56, v57
	v_cvt_pk_bf16_f32 v173, v58, v59
	v_cvt_pk_bf16_f32 v174, v48, v49
	v_cvt_pk_bf16_f32 v175, v50, v51
	global_store_dwordx4 v168, v[172:175], s[100:101]
	v_fmamk_f32 v162, v253, 0x3a800000, v188
	v_rsq_f32_e32 v162, v162
	v_add_u32_e32 v168, 0xc6000, v161
	v_pk_mul_f32 v[40:41], v[40:41], v[162:163] op_sel_hi:[1,0]
; __device__ __forceinline__ u32x4 pack8(const f32x4 a, const f32x4 b) { u32x4 w; w.x = cvt_pk_bf16(a[0], a[1]); w.y = cvt_pk_bf16(a[2], a[3]); w.z = cvt_pk_bf16(b[0], b[1]); w.w = cvt_pk_bf16(b[2], b[3]); return w; }
; __device__ __forceinline__ float sigmoidf_(float x) { return __builtin_amdgcn_rcpf(1.0f + __expf(-x)); }
; __device__ __forceinline__ float siluf_(float x) { return x * sigmoidf_(x); }
; __device__ __forceinline__ float rinv_of(float ssq) { return rsqrtf(ssq * (1.0f / 1024.0f) + EPS); }
;     __device__ __forceinline__ void operator()(const AccT& acc, const pg8::Unit& u, int wr, int wc, int fr, int fq) const {
;     ...
;             for (int m = 0; m < 4; ++m) ris[ai][m] = ssq_in[EPI_ROW(u, ai, m)];
; #pragma unroll
;         for (int ai = 0; ai < 2; ++ai)
; #pragma unroll
;             for (int m = 0; m < 4; ++m) {
;                 const int r = EPI_ROW(u, ai, m); const float ri = rinv_of(ris[ai][m]);
;                 f32x4 o[2];
; #pragma unroll
;                 for (int n = 0; n < 2; ++n) { const f32x4 gt = acc[ai][0][m][n] * ri, up = acc[ai][1][m][n] * ri;
; #pragma unroll
;                     for (int j = 0; j < 4; ++j) o[n][j] = siluf_(gt[j]) * up[j]; }
;                 *(u32x4*)(act + (size_t)r * DFF + u.pn * 128 + wc * 32 + 8 * fq) = pack8(o[0], o[1]); }
	v_pk_mul_f32 v[44:45], v[44:45], v[162:163] op_sel_hi:[1,0]
	v_pk_mul_f32 v[42:43], v[42:43], v[162:163] op_sel_hi:[1,0]
	v_pk_mul_f32 v[46:47], v[46:47], v[162:163] op_sel_hi:[1,0]
	v_mul_f32_e32 v164, 0xbfb8aa3b, v40
	v_mul_f32_e32 v165, 0xbfb8aa3b, v41
	v_mul_f32_e32 v166, 0xbfb8aa3b, v42
	v_mul_f32_e32 v167, 0xbfb8aa3b, v43
	v_exp_f32_e32 v164, v164
	v_exp_f32_e32 v165, v165
	v_exp_f32_e32 v166, v166
	v_exp_f32_e32 v167, v167
	v_add_f32_e32 v164, 1.0, v164
	v_add_f32_e32 v165, 1.0, v165
	v_add_f32_e32 v166, 1.0, v166
	v_add_f32_e32 v167, 1.0, v167
	v_rcp_f32_e32 v164, v164
	v_rcp_f32_e32 v165, v165
	v_rcp_f32_e32 v166, v166
	v_rcp_f32_e32 v167, v167
	s_nop 0
	v_pk_mul_f32 v[40:41], v[40:41], v[164:165]
	v_pk_mul_f32 v[42:43], v[42:43], v[166:167]
	v_pk_mul_f32 v[40:41], v[40:41], v[44:45]
	v_pk_mul_f32 v[42:43], v[42:43], v[46:47]
	v_pk_mul_f32 v[32:33], v[32:33], v[162:163] op_sel_hi:[1,0]
	v_pk_mul_f32 v[36:37], v[36:37], v[162:163] op_sel_hi:[1,0]
	v_pk_mul_f32 v[34:35], v[34:35], v[162:163] op_sel_hi:[1,0]
	v_pk_mul_f32 v[38:39], v[38:39], v[162:163] op_sel_hi:[1,0]
	v_mul_f32_e32 v164, 0xbfb8aa3b, v32
	v_mul_f32_e32 v165, 0xbfb8aa3b, v33
	v_mul_f32_e32 v166, 0xbfb8aa3b, v34
	v_mul_f32_e32 v167, 0xbfb8aa3b, v35
	v_exp_f32_e32 v164, v164
	v_exp_f32_e32 v165, v165
	v_exp_f32_e32 v166, v166
	v_exp_f32_e32 v167, v167
	v_add_f32_e32 v164, 1.0, v164
	v_add_f32_e32 v165, 1.0, v165
	v_add_f32_e32 v166, 1.0, v166
	v_add_f32_e32 v167, 1.0, v167
	v_rcp_f32_e32 v164, v164
	v_rcp_f32_e32 v165, v165
	v_rcp_f32_e32 v166, v166
	v_rcp_f32_e32 v167, v167
	s_nop 0
	v_pk_mul_f32 v[32:33], v[32:33], v[164:165]
	v_pk_mul_f32 v[34:35], v[34:35], v[166:167]
	v_pk_mul_f32 v[32:33], v[32:33], v[36:37]
	v_pk_mul_f32 v[34:35], v[34:35], v[38:39]
	v_cvt_pk_bf16_f32 v176, v40, v41
	v_cvt_pk_bf16_f32 v177, v42, v43
	v_cvt_pk_bf16_f32 v178, v32, v33
	v_cvt_pk_bf16_f32 v179, v34, v35
	global_store_dwordx4 v168, v[176:179], s[100:101]
	v_fmamk_f32 v162, v254, 0x3a800000, v188
	v_rsq_f32_e32 v162, v162
	v_add_u32_e32 v168, 0xdc000, v161
	v_pk_mul_f32 v[24:25], v[24:25], v[162:163] op_sel_hi:[1,0]
	v_pk_mul_f32 v[28:29], v[28:29], v[162:163] op_sel_hi:[1,0]
	v_pk_mul_f32 v[26:27], v[26:27], v[162:163] op_sel_hi:[1,0]
	v_pk_mul_f32 v[30:31], v[30:31], v[162:163] op_sel_hi:[1,0]
	v_mul_f32_e32 v164, 0xbfb8aa3b, v24
	v_mul_f32_e32 v165, 0xbfb8aa3b, v25
	v_mul_f32_e32 v166, 0xbfb8aa3b, v26
	v_mul_f32_e32 v167, 0xbfb8aa3b, v27
	v_exp_f32_e32 v164, v164
	v_exp_f32_e32 v165, v165
	v_exp_f32_e32 v166, v166
	v_exp_f32_e32 v167, v167
	v_add_f32_e32 v164, 1.0, v164
	v_add_f32_e32 v165, 1.0, v165
	v_add_f32_e32 v166, 1.0, v166
	v_add_f32_e32 v167, 1.0, v167
	v_rcp_f32_e32 v164, v164
	v_rcp_f32_e32 v165, v165
	v_rcp_f32_e32 v166, v166
	v_rcp_f32_e32 v167, v167
	s_nop 0
	v_pk_mul_f32 v[24:25], v[24:25], v[164:165]
	v_pk_mul_f32 v[26:27], v[26:27], v[166:167]
	v_pk_mul_f32 v[24:25], v[24:25], v[28:29]
	v_pk_mul_f32 v[26:27], v[26:27], v[30:31]
	v_pk_mul_f32 v[16:17], v[16:17], v[162:163] op_sel_hi:[1,0]
	v_pk_mul_f32 v[20:21], v[20:21], v[162:163] op_sel_hi:[1,0]
	v_pk_mul_f32 v[18:19], v[18:19], v[162:163] op_sel_hi:[1,0]
	v_pk_mul_f32 v[22:23], v[22:23], v[162:163] op_sel_hi:[1,0]
	v_mul_f32_e32 v164, 0xbfb8aa3b, v16
	v_mul_f32_e32 v165, 0xbfb8aa3b, v17
	v_mul_f32_e32 v166, 0xbfb8aa3b, v18
	v_mul_f32_e32 v167, 0xbfb8aa3b, v19
	v_exp_f32_e32 v164, v164
	v_exp_f32_e32 v165, v165
	v_exp_f32_e32 v166, v166
	v_exp_f32_e32 v167, v167
	v_add_f32_e32 v164, 1.0, v164
	v_add_f32_e32 v165, 1.0, v165
	v_add_f32_e32 v166, 1.0, v166
	v_add_f32_e32 v167, 1.0, v167
	v_rcp_f32_e32 v164, v164
	v_rcp_f32_e32 v165, v165
	v_rcp_f32_e32 v166, v166
	v_rcp_f32_e32 v167, v167
	s_nop 0
	v_pk_mul_f32 v[16:17], v[16:17], v[164:165]
	v_pk_mul_f32 v[18:19], v[18:19], v[166:167]
	v_pk_mul_f32 v[16:17], v[16:17], v[20:21]
	v_pk_mul_f32 v[18:19], v[18:19], v[22:23]
	v_cvt_pk_bf16_f32 v172, v24, v25
	v_cvt_pk_bf16_f32 v173, v26, v27
	v_cvt_pk_bf16_f32 v174, v16, v17
	v_cvt_pk_bf16_f32 v175, v18, v19
	global_store_dwordx4 v168, v[172:175], s[100:101]
	v_fmamk_f32 v162, v255, 0x3a800000, v188
	v_rsq_f32_e32 v162, v162
	v_add_u32_e32 v168, 0xf2000, v161
	v_pk_mul_f32 v[8:9], v[8:9], v[162:163] op_sel_hi:[1,0]
	v_pk_mul_f32 v[12:13], v[12:13], v[162:163] op_sel_hi:[1,0]
	v_pk_mul_f32 v[10:11], v[10:11], v[162:163] op_sel_hi:[1,0]
	v_pk_mul_f32 v[14:15], v[14:15], v[162:163] op_sel_hi:[1,0]
	v_mul_f32_e32 v164, 0xbfb8aa3b, v8
	v_mul_f32_e32 v165, 0xbfb8aa3b, v9
	v_mul_f32_e32 v166, 0xbfb8aa3b, v10
	v_mul_f32_e32 v167, 0xbfb8aa3b, v11
	v_exp_f32_e32 v164, v164
	v_exp_f32_e32 v165, v165
	v_exp_f32_e32 v166, v166
	v_exp_f32_e32 v167, v167
	v_add_f32_e32 v164, 1.0, v164
	v_add_f32_e32 v165, 1.0, v165
	v_add_f32_e32 v166, 1.0, v166
	v_add_f32_e32 v167, 1.0, v167
	v_rcp_f32_e32 v164, v164
	v_rcp_f32_e32 v165, v165
	v_rcp_f32_e32 v166, v166
	v_rcp_f32_e32 v167, v167
	s_nop 0
	v_pk_mul_f32 v[8:9], v[8:9], v[164:165]
	v_pk_mul_f32 v[10:11], v[10:11], v[166:167]
	v_pk_mul_f32 v[8:9], v[8:9], v[12:13]
	v_pk_mul_f32 v[10:11], v[10:11], v[14:15]
	v_pk_mul_f32 v[4:5], v[4:5], v[162:163] op_sel_hi:[1,0]
	v_pk_mul_f32 v[0:1], v[0:1], v[162:163] op_sel_hi:[1,0]
	v_pk_mul_f32 v[6:7], v[6:7], v[162:163] op_sel_hi:[1,0]
	v_pk_mul_f32 v[2:3], v[2:3], v[162:163] op_sel_hi:[1,0]
	v_mul_f32_e32 v164, 0xbfb8aa3b, v4
	v_mul_f32_e32 v165, 0xbfb8aa3b, v5
	v_mul_f32_e32 v166, 0xbfb8aa3b, v6
	v_mul_f32_e32 v167, 0xbfb8aa3b, v7
	v_exp_f32_e32 v164, v164
	v_exp_f32_e32 v165, v165
	v_exp_f32_e32 v166, v166
	v_exp_f32_e32 v167, v167
	v_add_f32_e32 v164, 1.0, v164
	v_add_f32_e32 v165, 1.0, v165
	v_add_f32_e32 v166, 1.0, v166
	v_add_f32_e32 v167, 1.0, v167
	v_rcp_f32_e32 v164, v164
	v_rcp_f32_e32 v165, v165
	v_rcp_f32_e32 v166, v166
	v_rcp_f32_e32 v167, v167
	s_nop 0
	v_pk_mul_f32 v[4:5], v[4:5], v[164:165]
	v_pk_mul_f32 v[6:7], v[6:7], v[166:167]
	v_pk_mul_f32 v[4:5], v[4:5], v[0:1]
	v_pk_mul_f32 v[6:7], v[6:7], v[2:3]
	v_cvt_pk_bf16_f32 v176, v8, v9
	v_cvt_pk_bf16_f32 v177, v10, v11
	v_cvt_pk_bf16_f32 v178, v4, v5
	v_cvt_pk_bf16_f32 v179, v6, v7
	global_store_dwordx4 v168, v[176:179], s[100:101]
	s_mov_b64 s[28:29], s[20:21]
	s_mov_b32 s25, s16
	s_mov_b32 s24, s18
	s_mov_b64 s[26:27], s[22:23]
	s_and_b64 vcc, exec, s[6:7]
	s_cbranch_vccnz .LBB0_2412
